# one static s_setprio 1 for the younger half (waves 4-7) at kernel entry, every per-MFMA-block s_setprio flip deleted (guide 7.4), on top of tail-fill conversion + nt
# speedup vs baseline: 1.0073x; 1.0000x over previous
_Z6mk_fwd4Args:
	s_load_dwordx4 s[28:31], s[0:1], 0x100
	s_load_dword s33, s[0:1], 0x110
	s_add_u32 s78, s0, 0x110
	s_mov_b32 s24, s2
	v_readfirstlane_b32 s2, v0
	s_addc_u32 s79, s1, 0
	v_cmp_gt_u32_e32 vcc, 64, v0
	v_writelane_b32 v252, s2, 0
	s_and_saveexec_b64 s[2:3], vcc
	v_lshl_add_u32 v1, v0, 2, 0
	v_add_u32_e32 v1, 0x26f00, v1
	v_mov_b32_e32 v2, 0
	ds_write_b32 v1, v2
	s_or_b64 exec, exec, s[2:3]
	v_readlane_b32 s2, v252, 0
	s_lshr_b32 s25, s2, 6
	s_cmp_lt_u32 s25, 4
	s_cbranch_scc1 .Lmy_prio_skip
	s_setprio 1
.Lmy_prio_skip:
	s_waitcnt lgkmcnt(0)
	s_min_i32 s2, s31, 0x64
	s_sub_i32 s4, s2, s30
	s_cmp_gt_i32 s4, 1
	s_cselect_b64 s[2:3], -1, 0
	s_add_u32 s72, s28, 0x4000
	s_addc_u32 s73, s29, 0
	s_cmp_lt_i32 s4, 2
	s_mov_b32 s75, 0
	v_cmp_eq_u32_e32 vcc, 0, v0
	s_mov_b32 s74, 0
	s_barrier
	v_writelane_b32 v252, s25, 1
	s_cbranch_scc1 .LBB0_7
	s_getreg_b32 s4, hwreg(HW_REG_XCC_ID, 0, 4)
	s_and_b32 s74, s4, 15
	v_readfirstlane_b32 s8, v0
	s_and_saveexec_b64 s[4:5], vcc
	s_cbranch_execz .LBB0_6
	s_mov_b64 s[6:7], exec
	v_mbcnt_lo_u32_b32 v1, s6, 0
	v_mbcnt_hi_u32_b32 v1, s7, v1
	v_cmp_eq_u32_e32 vcc, 0, v1
	s_and_b64 s[10:11], exec, vcc
	s_mov_b64 exec, s[10:11]
	s_cbranch_execz .LBB0_6
	s_lshl_b32 s9, s74, 8
	s_bcnt1_i32_b64 s6, s[6:7]
	v_mov_b32_e32 v1, s9
	v_mov_b32_e32 v2, s6
	global_atomic_add v1, v2, s[72:73] offset:1024
